# P1 dt_phase moved onto the 128 workgroups that have one GEMM tile fewer (16 vs 17); hg_unit fast path: lb-logit wait + 2-way softmax deferred behind the 64 row loads (vmcnt(63))
# baseline (speedup 1.0000x reference)
; __device__ __forceinline__ f32x4 mfma32(bf16x8 a, bf16x8 b, f32x4 c) { return __builtin_amdgcn_mfma_f32_16x16x32_bf16(a, b, c, 0, 0, 0); }
; __device__ __forceinline__ void dt_phase(const Ptrs& P, int gw, int NGW, int lane) {
;     const bf16_t* U = (const bf16_t*)(P.ws + WS_U); const bf16_t* WdtT = (const bf16_t*)((unsigned char*)P.out + DO_WDT); float* dtraw = (float*)((unsigned char*)P.out + DO_DTRAW);
;     const int lc = lane & 15, g = lane >> 4;
;     for (int it = gw; it < MTOK / 16; it += NGW) {
;         const int r0 = 16 * it; f32x4 acc = {0.f, 0.f, 0.f, 0.f};
;         const bf16_t* ap = U + (size_t)(r0 + lc) * DM + 8 * g; const bf16_t* bp = WdtT + (size_t)lc * DM + 8 * g;
; #pragma unroll 8
;         for (int ks = 0; ks < 64; ++ks) { const bf16x8 a = *(const bf16x8*)(ap + ks * 32); const bf16x8 b = *(const bf16x8*)(bp + ks * 32); acc = mfma32(a, b, acc); }
; #pragma unroll
;         for (int r = 0; r < 4; ++r) dtraw[(size_t)(r0 + 4 * g + r) * 16 + lc] = acc[r];
;     }
.LBB0_230:
	s_getreg_b32 s3, hwreg(HW_REG_HW_ID, 0, 6)
	s_and_b32 s3, s3, 63
	s_lshl_b32 s3, s3, 2
	s_add_i32 s3, s3, 0
	s_add_i32 s3, s3, 0x27ef0
	v_mov_b32_e32 v0, s3
	ds_read_b32 v0, v0
	s_mov_b64 s[6:7], s[0:1]
	s_waitcnt lgkmcnt(0)
	v_readfirstlane_b32 s3, v0
	s_nop 1
	v_lshl_add_u32 v1, s3, 6, v213
	v_readlane_b32 s3, v255, 18
	v_ashrrev_i32_e32 v0, 6, v1
	s_nop 0
	v_add_u32_e32 v14, s3, v0
	v_add_u32_e32 v14, 0xfffffc00, v14
	s_movk_i32 s3, 0x802
	v_cmp_gt_u32_e32 vcc, s3, v14
	s_and_saveexec_b64 s[4:5], vcc
	s_xor_b64 s[4:5], exec, s[4:5]
	s_cbranch_execz .LBB0_236
	global_load_dwordx4 v[8:11], v16, s[6:7] offset:176
	v_and_b32_e32 v5, 15, v1
	v_bfe_u32 v2, v1, 4, 2
	v_mov_b32_e32 v1, v16
	v_lshlrev_b32_e32 v4, 4, v0
	v_lshlrev_b32_e32 v15, 2, v2
	v_lshlrev_b32_e32 v0, 2, v5
	v_lshlrev_b32_e32 v2, 4, v2
	v_mov_b32_e32 v3, v16
	v_mov_b32_e32 v13, v16
	v_readlane_b32 s3, v255, 20
	v_lshl_or_b32 v12, v5, 12, v2
	s_mov_b64 s[6:7], 0xd300000
	v_add3_u32 v4, s3, v4, v5
	v_add_u32_e32 v4, 0xffffc000, v4
	s_waitcnt vmcnt(0)
	v_lshl_add_u64 v[0:1], v[8:9], 0, v[0:1]
	v_lshl_add_u64 v[6:7], v[10:11], 0, v[2:3]
	v_lshl_add_u64 v[8:9], v[8:9], 0, v[12:13]
	v_lshl_add_u64 v[10:11], v[0:1], 0, s[6:7]
	s_mov_b64 s[6:7], 0
	s_load_dwordx2 s[100:101], s[0:1], 0xb0
	v_and_b32_e32 v17, 15, v213
	v_lshrrev_b32_e32 v62, 4, v213
	v_and_b32_e32 v70, 3, v17
	v_xor_b32_e32 v70, v70, v62
	v_lshrrev_b32_e32 v72, 2, v17
	v_xor_b32_e32 v73, 0, v72
	v_lshl_or_b32 v73, v73, 2, v70
	v_lshlrev_b32_e32 v73, 4, v73
	v_lshl_add_u32 v73, v17, 12, v73
	v_xor_b32_e32 v90, 1, v72
	v_lshl_or_b32 v90, v90, 2, v70
	v_lshlrev_b32_e32 v90, 4, v90
	v_lshl_add_u32 v90, v17, 12, v90
	v_xor_b32_e32 v91, 2, v72
	v_lshl_or_b32 v91, v91, 2, v70
	v_lshlrev_b32_e32 v91, 4, v91
	v_lshl_add_u32 v91, v17, 12, v91
	v_xor_b32_e32 v124, 3, v72
	v_lshl_or_b32 v124, v124, 2, v70
	v_lshlrev_b32_e32 v124, 4, v124
	v_lshl_add_u32 v124, v17, 12, v124
	v_and_b32_e32 v125, 7, v14
	v_lshlrev_b32_e32 v125, 1, v125
	s_waitcnt lgkmcnt(0)
	s_add_u32 s100, s100, 0x8f00000
	s_addc_u32 s101, s101, 0
	v_xor_b32_e32 v192, v125, v213
	v_lshlrev_b32_e32 v192, 4, v192
	v_lshl_add_u32 v192, v125, 12, v192
	global_load_dwordx4 v[76:79], v192, s[100:101]
	global_load_dwordx4 v[80:83], v192, s[100:101] offset:1024
	global_load_dwordx4 v[84:87], v192, s[100:101] offset:2048
	global_load_dwordx4 v[92:95], v192, s[100:101] offset:3072
	v_add_u32_e32 v125, 1, v125
	v_xor_b32_e32 v192, v125, v213
	v_lshlrev_b32_e32 v192, 4, v192
	v_lshl_add_u32 v192, v125, 12, v192
	global_load_dwordx4 v[96:99], v192, s[100:101]
	global_load_dwordx4 v[100:103], v192, s[100:101] offset:1024
	global_load_dwordx4 v[104:107], v192, s[100:101] offset:2048
	global_load_dwordx4 v[112:115], v192, s[100:101] offset:3072
	s_waitcnt vmcnt(0)
	v_lshlrev_b32_e32 v193, 4, v213
	v_add_u32_e32 v192, -1, v125
	v_lshl_add_u32 v193, v192, 12, v193
	ds_write_b128 v193, v[76:79]
	ds_write_b128 v193, v[80:83] offset:1024
	ds_write_b128 v193, v[84:87] offset:2048
	ds_write_b128 v193, v[92:95] offset:3072
	v_lshlrev_b32_e32 v193, 4, v213
	v_add_u32_e32 v192, 0, v125
	v_lshl_add_u32 v193, v192, 12, v193
	ds_write_b128 v193, v[96:99]
	ds_write_b128 v193, v[100:103] offset:1024
	ds_write_b128 v193, v[104:107] offset:2048
	ds_write_b128 v193, v[112:115] offset:3072
	s_waitcnt lgkmcnt(0)
	s_barrier

; __device__ __forceinline__ f32x4 mfma32(bf16x8 a, bf16x8 b, f32x4 c) { return __builtin_amdgcn_mfma_f32_16x16x32_bf16(a, b, c, 0, 0, 0); }
; __device__ __forceinline__ void dt_phase(const Ptrs& P, int gw, int NGW, int lane) {
;     ...
; #pragma unroll 8
;         for (int ks = 0; ks < 64; ++ks) { const bf16x8 a = *(const bf16x8*)(ap + ks * 32); const bf16x8 b = *(const bf16x8*)(bp + ks * 32); acc = mfma32(a, b, acc); }
.LBB0_233:
	s_mov_b64 s[100:101], 0x10300000
	v_lshl_add_u64 v[214:215], v[12:13], 0, s[100:101]
	global_load_dwordx4 v[76:79], v[214:215], off
	ds_read_b128 v[152:155], v73
	global_load_dwordx4 v[80:83], v[214:215], off offset:64
	ds_read_b128 v[156:159], v90
	global_load_dwordx4 v[84:87], v[214:215], off offset:128
	ds_read_b128 v[160:163], v91
	global_load_dwordx4 v[92:95], v[214:215], off offset:192
	ds_read_b128 v[164:167], v124
	global_load_dwordx4 v[96:99], v[214:215], off offset:256
	ds_read_b128 v[168:171], v73 offset:256
	global_load_dwordx4 v[100:103], v[214:215], off offset:320
	ds_read_b128 v[172:175], v90 offset:256
	global_load_dwordx4 v[104:107], v[214:215], off offset:384
	ds_read_b128 v[176:179], v91 offset:256
	global_load_dwordx4 v[112:115], v[214:215], off offset:448
	ds_read_b128 v[180:183], v124 offset:256
	global_load_dwordx4 v[116:119], v[214:215], off offset:512
	ds_read_b128 v[184:187], v73 offset:512
	global_load_dwordx4 v[120:123], v[214:215], off offset:576
	ds_read_b128 v[188:191], v90 offset:512
	global_load_dwordx4 v[128:131], v[214:215], off offset:640
	ds_read_b128 v[196:199], v91 offset:512
	global_load_dwordx4 v[132:135], v[214:215], off offset:704
	ds_read_b128 v[200:203], v124 offset:512
	global_load_dwordx4 v[136:139], v[214:215], off offset:768
	ds_read_b128 v[204:207], v73 offset:768
	global_load_dwordx4 v[140:143], v[214:215], off offset:832
	ds_read_b128 v[208:211], v90 offset:768
	global_load_dwordx4 v[144:147], v[214:215], off offset:896
	ds_read_b128 v[216:219], v91 offset:768
	global_load_dwordx4 v[148:151], v[214:215], off offset:960
	ds_read_b128 v[220:223], v124 offset:768
	s_waitcnt vmcnt(15) lgkmcnt(15)
	v_mfma_f32_16x16x32_bf16 v[0:3], v[76:79], v[152:155], v[0:3]
	s_waitcnt vmcnt(14) lgkmcnt(14)
	v_mfma_f32_16x16x32_bf16 v[0:3], v[80:83], v[156:159], v[0:3]
	s_waitcnt vmcnt(13) lgkmcnt(13)
	v_mfma_f32_16x16x32_bf16 v[0:3], v[84:87], v[160:163], v[0:3]
	s_waitcnt vmcnt(12) lgkmcnt(12)
	v_mfma_f32_16x16x32_bf16 v[0:3], v[92:95], v[164:167], v[0:3]
	s_waitcnt vmcnt(11) lgkmcnt(11)
	v_mfma_f32_16x16x32_bf16 v[0:3], v[96:99], v[168:171], v[0:3]
	s_waitcnt vmcnt(10) lgkmcnt(10)
	v_mfma_f32_16x16x32_bf16 v[0:3], v[100:103], v[172:175], v[0:3]
	s_waitcnt vmcnt(9) lgkmcnt(9)
	v_mfma_f32_16x16x32_bf16 v[0:3], v[104:107], v[176:179], v[0:3]
	s_waitcnt vmcnt(8) lgkmcnt(8)
	v_mfma_f32_16x16x32_bf16 v[0:3], v[112:115], v[180:183], v[0:3]
	global_load_dwordx4 v[76:79], v[214:215], off offset:1024
	ds_read_b128 v[152:155], v73 offset:1024
	global_load_dwordx4 v[80:83], v[214:215], off offset:1088
	ds_read_b128 v[156:159], v90 offset:1024
	global_load_dwordx4 v[84:87], v[214:215], off offset:1152
	ds_read_b128 v[160:163], v91 offset:1024
	global_load_dwordx4 v[92:95], v[214:215], off offset:1216
	ds_read_b128 v[164:167], v124 offset:1024
	global_load_dwordx4 v[96:99], v[214:215], off offset:1280
	ds_read_b128 v[168:171], v73 offset:1280
	global_load_dwordx4 v[100:103], v[214:215], off offset:1344
	ds_read_b128 v[172:175], v90 offset:1280
	global_load_dwordx4 v[104:107], v[214:215], off offset:1408
	ds_read_b128 v[176:179], v91 offset:1280
	global_load_dwordx4 v[112:115], v[214:215], off offset:1472
	ds_read_b128 v[180:183], v124 offset:1280
	s_waitcnt vmcnt(15) lgkmcnt(15)
	v_mfma_f32_16x16x32_bf16 v[0:3], v[116:119], v[184:187], v[0:3]
	s_waitcnt vmcnt(14) lgkmcnt(14)
	v_mfma_f32_16x16x32_bf16 v[0:3], v[120:123], v[188:191], v[0:3]
	s_waitcnt vmcnt(13) lgkmcnt(13)
	v_mfma_f32_16x16x32_bf16 v[0:3], v[128:131], v[196:199], v[0:3]
	s_waitcnt vmcnt(12) lgkmcnt(12)
	v_mfma_f32_16x16x32_bf16 v[0:3], v[132:135], v[200:203], v[0:3]
	s_waitcnt vmcnt(11) lgkmcnt(11)
	v_mfma_f32_16x16x32_bf16 v[0:3], v[136:139], v[204:207], v[0:3]
	s_waitcnt vmcnt(10) lgkmcnt(10)
	v_mfma_f32_16x16x32_bf16 v[0:3], v[140:143], v[208:211], v[0:3]
	s_waitcnt vmcnt(9) lgkmcnt(9)
	v_mfma_f32_16x16x32_bf16 v[0:3], v[144:147], v[216:219], v[0:3]
	s_waitcnt vmcnt(8) lgkmcnt(8)
	v_mfma_f32_16x16x32_bf16 v[0:3], v[148:151], v[220:223], v[0:3]
	global_load_dwordx4 v[116:119], v[214:215], off offset:1536
	ds_read_b128 v[184:187], v73 offset:1536
	global_load_dwordx4 v[120:123], v[214:215], off offset:1600
	ds_read_b128 v[188:191], v90 offset:1536
	global_load_dwordx4 v[128:131], v[214:215], off offset:1664
	ds_read_b128 v[196:199], v91 offset:1536
	global_load_dwordx4 v[132:135], v[214:215], off offset:1728
	ds_read_b128 v[200:203], v124 offset:1536
	global_load_dwordx4 v[136:139], v[214:215], off offset:1792
	ds_read_b128 v[204:207], v73 offset:1792
	global_load_dwordx4 v[140:143], v[214:215], off offset:1856
	ds_read_b128 v[208:211], v90 offset:1792
	global_load_dwordx4 v[144:147], v[214:215], off offset:1920
	ds_read_b128 v[216:219], v91 offset:1792
	global_load_dwordx4 v[148:151], v[214:215], off offset:1984
	ds_read_b128 v[220:223], v124 offset:1792
	s_waitcnt vmcnt(15) lgkmcnt(15)
	v_mfma_f32_16x16x32_bf16 v[0:3], v[76:79], v[152:155], v[0:3]
	s_waitcnt vmcnt(14) lgkmcnt(14)
	v_mfma_f32_16x16x32_bf16 v[0:3], v[80:83], v[156:159], v[0:3]
	s_waitcnt vmcnt(13) lgkmcnt(13)
	v_mfma_f32_16x16x32_bf16 v[0:3], v[84:87], v[160:163], v[0:3]
	s_waitcnt vmcnt(12) lgkmcnt(12)
	v_mfma_f32_16x16x32_bf16 v[0:3], v[92:95], v[164:167], v[0:3]
	s_waitcnt vmcnt(11) lgkmcnt(11)
	v_mfma_f32_16x16x32_bf16 v[0:3], v[96:99], v[168:171], v[0:3]
	s_waitcnt vmcnt(10) lgkmcnt(10)
	v_mfma_f32_16x16x32_bf16 v[0:3], v[100:103], v[172:175], v[0:3]
	s_waitcnt vmcnt(9) lgkmcnt(9)
	v_mfma_f32_16x16x32_bf16 v[0:3], v[104:107], v[176:179], v[0:3]
	s_waitcnt vmcnt(8) lgkmcnt(8)
; __device__ __forceinline__ f32x4 mfma32(bf16x8 a, bf16x8 b, f32x4 c) { return __builtin_amdgcn_mfma_f32_16x16x32_bf16(a, b, c, 0, 0, 0); }
; __device__ __forceinline__ void dt_phase(const Ptrs& P, int gw, int NGW, int lane) {
;     ...
; #pragma unroll 8
;         for (int ks = 0; ks < 64; ++ks) { const bf16x8 a = *(const bf16x8*)(ap + ks * 32); const bf16x8 b = *(const bf16x8*)(bp + ks * 32); acc = mfma32(a, b, acc); }
	v_mfma_f32_16x16x32_bf16 v[0:3], v[112:115], v[180:183], v[0:3]
	global_load_dwordx4 v[76:79], v[214:215], off offset:2048
	ds_read_b128 v[152:155], v73 offset:2048
	global_load_dwordx4 v[80:83], v[214:215], off offset:2112
	ds_read_b128 v[156:159], v90 offset:2048
	global_load_dwordx4 v[84:87], v[214:215], off offset:2176
	ds_read_b128 v[160:163], v91 offset:2048
	global_load_dwordx4 v[92:95], v[214:215], off offset:2240
	ds_read_b128 v[164:167], v124 offset:2048
	global_load_dwordx4 v[96:99], v[214:215], off offset:2304
	ds_read_b128 v[168:171], v73 offset:2304
	global_load_dwordx4 v[100:103], v[214:215], off offset:2368
	ds_read_b128 v[172:175], v90 offset:2304
	global_load_dwordx4 v[104:107], v[214:215], off offset:2432
	ds_read_b128 v[176:179], v91 offset:2304
	global_load_dwordx4 v[112:115], v[214:215], off offset:2496
	ds_read_b128 v[180:183], v124 offset:2304
	s_waitcnt vmcnt(15) lgkmcnt(15)
	v_mfma_f32_16x16x32_bf16 v[0:3], v[116:119], v[184:187], v[0:3]
	s_waitcnt vmcnt(14) lgkmcnt(14)
	v_mfma_f32_16x16x32_bf16 v[0:3], v[120:123], v[188:191], v[0:3]
	s_waitcnt vmcnt(13) lgkmcnt(13)
	v_mfma_f32_16x16x32_bf16 v[0:3], v[128:131], v[196:199], v[0:3]
	s_waitcnt vmcnt(12) lgkmcnt(12)
	v_mfma_f32_16x16x32_bf16 v[0:3], v[132:135], v[200:203], v[0:3]
	s_waitcnt vmcnt(11) lgkmcnt(11)
	v_mfma_f32_16x16x32_bf16 v[0:3], v[136:139], v[204:207], v[0:3]
	s_waitcnt vmcnt(10) lgkmcnt(10)
	v_mfma_f32_16x16x32_bf16 v[0:3], v[140:143], v[208:211], v[0:3]
	s_waitcnt vmcnt(9) lgkmcnt(9)
	v_mfma_f32_16x16x32_bf16 v[0:3], v[144:147], v[216:219], v[0:3]
	s_waitcnt vmcnt(8) lgkmcnt(8)
	v_mfma_f32_16x16x32_bf16 v[0:3], v[148:151], v[220:223], v[0:3]
	global_load_dwordx4 v[116:119], v[214:215], off offset:2560
	ds_read_b128 v[184:187], v73 offset:2560
	global_load_dwordx4 v[120:123], v[214:215], off offset:2624
	ds_read_b128 v[188:191], v90 offset:2560
	global_load_dwordx4 v[128:131], v[214:215], off offset:2688
	ds_read_b128 v[196:199], v91 offset:2560
	global_load_dwordx4 v[132:135], v[214:215], off offset:2752
	ds_read_b128 v[200:203], v124 offset:2560
	global_load_dwordx4 v[136:139], v[214:215], off offset:2816
	ds_read_b128 v[204:207], v73 offset:2816
	global_load_dwordx4 v[140:143], v[214:215], off offset:2880
	ds_read_b128 v[208:211], v90 offset:2816
	global_load_dwordx4 v[144:147], v[214:215], off offset:2944
	ds_read_b128 v[216:219], v91 offset:2816
	global_load_dwordx4 v[148:151], v[214:215], off offset:3008
	ds_read_b128 v[220:223], v124 offset:2816
	s_waitcnt vmcnt(15) lgkmcnt(15)
	v_mfma_f32_16x16x32_bf16 v[0:3], v[76:79], v[152:155], v[0:3]
	s_waitcnt vmcnt(14) lgkmcnt(14)
	v_mfma_f32_16x16x32_bf16 v[0:3], v[80:83], v[156:159], v[0:3]
	s_waitcnt vmcnt(13) lgkmcnt(13)
	v_mfma_f32_16x16x32_bf16 v[0:3], v[84:87], v[160:163], v[0:3]
	s_waitcnt vmcnt(12) lgkmcnt(12)
	v_mfma_f32_16x16x32_bf16 v[0:3], v[92:95], v[164:167], v[0:3]
	s_waitcnt vmcnt(11) lgkmcnt(11)
	v_mfma_f32_16x16x32_bf16 v[0:3], v[96:99], v[168:171], v[0:3]
	s_waitcnt vmcnt(10) lgkmcnt(10)
	v_mfma_f32_16x16x32_bf16 v[0:3], v[100:103], v[172:175], v[0:3]
	s_waitcnt vmcnt(9) lgkmcnt(9)
	v_mfma_f32_16x16x32_bf16 v[0:3], v[104:107], v[176:179], v[0:3]
	s_waitcnt vmcnt(8) lgkmcnt(8)
	v_mfma_f32_16x16x32_bf16 v[0:3], v[112:115], v[180:183], v[0:3]
	global_load_dwordx4 v[76:79], v[214:215], off offset:3072
	ds_read_b128 v[152:155], v73 offset:3072
	global_load_dwordx4 v[80:83], v[214:215], off offset:3136
	ds_read_b128 v[156:159], v90 offset:3072
	global_load_dwordx4 v[84:87], v[214:215], off offset:3200
	ds_read_b128 v[160:163], v91 offset:3072
	global_load_dwordx4 v[92:95], v[214:215], off offset:3264
	ds_read_b128 v[164:167], v124 offset:3072
	global_load_dwordx4 v[96:99], v[214:215], off offset:3328
	ds_read_b128 v[168:171], v73 offset:3328
	global_load_dwordx4 v[100:103], v[214:215], off offset:3392
	ds_read_b128 v[172:175], v90 offset:3328
	global_load_dwordx4 v[104:107], v[214:215], off offset:3456
	ds_read_b128 v[176:179], v91 offset:3328
	global_load_dwordx4 v[112:115], v[214:215], off offset:3520
	ds_read_b128 v[180:183], v124 offset:3328
	s_waitcnt vmcnt(15) lgkmcnt(15)
; __device__ __forceinline__ f32x4 mfma32(bf16x8 a, bf16x8 b, f32x4 c) { return __builtin_amdgcn_mfma_f32_16x16x32_bf16(a, b, c, 0, 0, 0); }
; __device__ __forceinline__ void dt_phase(const Ptrs& P, int gw, int NGW, int lane) {
;     ...
;         for (int ks = 0; ks < 64; ++ks) { const bf16x8 a = *(const bf16x8*)(ap + ks * 32); const bf16x8 b = *(const bf16x8*)(bp + ks * 32); acc = mfma32(a, b, acc); }
; #pragma unroll
;         for (int r = 0; r < 4; ++r) dtraw[(size_t)(r0 + 4 * g + r) * 16 + lc] = acc[r];
;     }
	v_mfma_f32_16x16x32_bf16 v[0:3], v[116:119], v[184:187], v[0:3]
	s_waitcnt vmcnt(14) lgkmcnt(14)
	v_mfma_f32_16x16x32_bf16 v[0:3], v[120:123], v[188:191], v[0:3]
	s_waitcnt vmcnt(13) lgkmcnt(13)
	v_mfma_f32_16x16x32_bf16 v[0:3], v[128:131], v[196:199], v[0:3]
	s_waitcnt vmcnt(12) lgkmcnt(12)
	v_mfma_f32_16x16x32_bf16 v[0:3], v[132:135], v[200:203], v[0:3]
	s_waitcnt vmcnt(11) lgkmcnt(11)
	v_mfma_f32_16x16x32_bf16 v[0:3], v[136:139], v[204:207], v[0:3]
	s_waitcnt vmcnt(10) lgkmcnt(10)
	v_mfma_f32_16x16x32_bf16 v[0:3], v[140:143], v[208:211], v[0:3]
	s_waitcnt vmcnt(9) lgkmcnt(9)
	v_mfma_f32_16x16x32_bf16 v[0:3], v[144:147], v[216:219], v[0:3]
	s_waitcnt vmcnt(8) lgkmcnt(8)
	v_mfma_f32_16x16x32_bf16 v[0:3], v[148:151], v[220:223], v[0:3]
	global_load_dwordx4 v[116:119], v[214:215], off offset:3584
	ds_read_b128 v[184:187], v73 offset:3584
	global_load_dwordx4 v[120:123], v[214:215], off offset:3648
	ds_read_b128 v[188:191], v90 offset:3584
	global_load_dwordx4 v[128:131], v[214:215], off offset:3712
	ds_read_b128 v[196:199], v91 offset:3584
	global_load_dwordx4 v[132:135], v[214:215], off offset:3776
	ds_read_b128 v[200:203], v124 offset:3584
	global_load_dwordx4 v[136:139], v[214:215], off offset:3840
	ds_read_b128 v[204:207], v73 offset:3840
	global_load_dwordx4 v[140:143], v[214:215], off offset:3904
	ds_read_b128 v[208:211], v90 offset:3840
	global_load_dwordx4 v[144:147], v[214:215], off offset:3968
	ds_read_b128 v[216:219], v91 offset:3840
	global_load_dwordx4 v[148:151], v[214:215], off offset:4032
	ds_read_b128 v[220:223], v124 offset:3840
	s_waitcnt vmcnt(15) lgkmcnt(15)
	v_mfma_f32_16x16x32_bf16 v[0:3], v[76:79], v[152:155], v[0:3]
	s_waitcnt vmcnt(14) lgkmcnt(14)
	v_mfma_f32_16x16x32_bf16 v[0:3], v[80:83], v[156:159], v[0:3]
	s_waitcnt vmcnt(13) lgkmcnt(13)
	v_mfma_f32_16x16x32_bf16 v[0:3], v[84:87], v[160:163], v[0:3]
	s_waitcnt vmcnt(12) lgkmcnt(12)
	v_mfma_f32_16x16x32_bf16 v[0:3], v[92:95], v[164:167], v[0:3]
	s_waitcnt vmcnt(11) lgkmcnt(11)
	v_mfma_f32_16x16x32_bf16 v[0:3], v[96:99], v[168:171], v[0:3]
	s_waitcnt vmcnt(10) lgkmcnt(10)
	v_mfma_f32_16x16x32_bf16 v[0:3], v[100:103], v[172:175], v[0:3]
	s_waitcnt vmcnt(9) lgkmcnt(9)
	v_mfma_f32_16x16x32_bf16 v[0:3], v[104:107], v[176:179], v[0:3]
	s_waitcnt vmcnt(8) lgkmcnt(8)
	v_mfma_f32_16x16x32_bf16 v[0:3], v[112:115], v[180:183], v[0:3]
	s_waitcnt vmcnt(7) lgkmcnt(7)
	v_mfma_f32_16x16x32_bf16 v[0:3], v[116:119], v[184:187], v[0:3]
	s_waitcnt vmcnt(6) lgkmcnt(6)
	v_mfma_f32_16x16x32_bf16 v[0:3], v[120:123], v[188:191], v[0:3]
	s_waitcnt vmcnt(5) lgkmcnt(5)
	v_mfma_f32_16x16x32_bf16 v[0:3], v[128:131], v[196:199], v[0:3]
	s_waitcnt vmcnt(4) lgkmcnt(4)
	v_mfma_f32_16x16x32_bf16 v[0:3], v[132:135], v[200:203], v[0:3]
	s_waitcnt vmcnt(3) lgkmcnt(3)
	v_mfma_f32_16x16x32_bf16 v[0:3], v[136:139], v[204:207], v[0:3]
	s_waitcnt vmcnt(2) lgkmcnt(2)
	v_mfma_f32_16x16x32_bf16 v[0:3], v[140:143], v[208:211], v[0:3]
	s_waitcnt vmcnt(1) lgkmcnt(1)
	v_mfma_f32_16x16x32_bf16 v[0:3], v[144:147], v[216:219], v[0:3]
	s_waitcnt vmcnt(0) lgkmcnt(0)
	v_mfma_f32_16x16x32_bf16 v[0:3], v[148:151], v[220:223], v[0:3]
	s_nop 7
	v_lshl_or_b32 v12, v14, 4, v15
	v_ashrrev_i32_e32 v13, 31, v12
	v_lshlrev_b64 v[18:19], 6, v[12:13]
	v_lshl_add_u64 v[18:19], v[10:11], 0, v[18:19]
	s_nop 2
	global_store_dword v[18:19], v0, off
	v_or_b32_e32 v18, 1, v12
	v_ashrrev_i32_e32 v19, 31, v18
	v_lshlrev_b64 v[18:19], 6, v[18:19]
	v_lshl_add_u64 v[18:19], v[10:11], 0, v[18:19]
	v_or_b32_e32 v0, 2, v12
	global_store_dword v[18:19], v1, off
	v_ashrrev_i32_e32 v1, 31, v0
	v_lshlrev_b64 v[0:1], 6, v[0:1]
	v_lshl_add_u64 v[0:1], v[10:11], 0, v[0:1]
	global_store_dword v[0:1], v2, off
	v_or_b32_e32 v0, 3, v12
	v_ashrrev_i32_e32 v1, 31, v0
	v_lshlrev_b64 v[0:1], 6, v[0:1]
	v_lshl_add_u64 v[0:1], v[10:11], 0, v[0:1]
	global_store_dword v[0:1], v3, off
	v_add_u32_e32 v0, 0x400, v14
	v_cmp_lt_i32_e32 vcc, 0x401, v14
	v_add_u32_e32 v4, 0x4000, v4
	s_or_b64 s[6:7], vcc, s[6:7]
	v_mov_b32_e32 v14, v0
	s_andn2_b64 exec, exec, s[6:7]
	s_cbranch_execnz .LBB0_232
	s_or_b64 exec, exec, s[6:7]

; __device__ __forceinline__ void hg_unit(const Ptrs& P, int l, int b, int hd, int ch, unsigned char* lds, int tid) {
;     ...
;         if (l == 1) { const float a0 = P.lb_logits[hd * 128 + dk], a1 = P.lb_logits[1024 + hd * 128 + dk]; const float mxx = fmaxf(a0, a1); const float e0 = __expf(a0 - mxx), e1 = __expf(a1 - mxx);
;             lb = e1 / (e0 + e1); lb = fminf(fmaxf(lb, 0.f), 1.0f - 1e-4f); }
;         bf16_t hfv[2][16], hqv[2][16];
; #pragma unroll
;         for (int jj = 0; jj < 2; ++jj) { const int j = 2 * sg + jj;
; #pragma unroll
;             for (int t = 0; t < 16; ++t) { hfv[jj][t] = 0; hqv[jj][t] = 0;
;                 if (j < nsub) { const bf16_t* rp = PJ + (row0 + 16 * j + t) * PW + hd * 128 + dk; hfv[jj][t] = rp[C_HF]; hqv[jj][t] = rp[C_HQ]; } } }
.LBB0_523:
	v_readlane_b32 s6, v255, 36
	v_readlane_b32 s7, v255, 37
	v_and_b32_e32 v11, 0x7f, v98
	v_mov_b32_e32 v38, 0
	s_andn2_b64 vcc, exec, s[6:7]
	v_mov_b32_e32 v32, 0
	s_cbranch_vccnz .LBB0_525
	v_or_b32_e32 v32, s3, v11
	v_lshlrev_b32_e32 v32, 2, v32
	v_mov_b32_e32 v33, v16
	v_lshl_add_u64 v[34:35], v[2:3], 0, v[32:33]
	v_readfirstlane_b32 s6, v2
	v_readfirstlane_b32 s7, v3
	s_nop 4
	global_load_dword v214, v32, s[6:7]
	v_add_co_u32_e32 v32, vcc, 0x1000, v34
	s_nop 1
	v_addc_co_u32_e32 v33, vcc, 0, v35, vcc
	global_load_dword v215, v[32:33], off
	s_and_b64 vcc, exec, s[76:77]
	s_cbranch_vccnz .LBB0_525
	s_waitcnt vmcnt(1)
	v_max_f32_e32 v34, v214, v214
	s_waitcnt vmcnt(0)
	v_max_f32_e32 v33, v215, v215
	v_max_f32_e32 v33, v34, v33
	v_sub_f32_e32 v34, v214, v33
	v_sub_f32_e32 v32, v215, v33
	v_mul_f32_e32 v34, 0x3fb8aa3b, v34
	v_mul_f32_e32 v32, 0x3fb8aa3b, v32
	v_exp_f32_e32 v34, v34
	v_exp_f32_e32 v32, v32
	s_nop 0
	v_add_f32_e32 v33, v34, v32
	v_div_scale_f32 v34, s[6:7], v33, v33, v32
	v_rcp_f32_e32 v35, v34
	s_nop 0
	v_fma_f32 v36, -v34, v35, 1.0
	v_fmac_f32_e32 v35, v36, v35
	v_div_scale_f32 v36, vcc, v32, v33, v32
	v_mul_f32_e32 v37, v36, v35
	v_fma_f32 v39, -v34, v37, v36
	v_fmac_f32_e32 v37, v39, v35
	v_fma_f32 v34, -v34, v37, v36
	v_div_fmas_f32 v34, v34, v35, v37
	v_div_fixup_f32 v32, v34, v33, v32
	v_max_f32_e32 v32, 0, v32
	v_min_f32_e32 v32, 0x3f7ff972, v32
.LBB0_525:
	v_and_b32_e32 v33, -2, v107
	v_lshl_add_u64 v[34:35], v[86:87], 0, s[96:97]
	v_lshlrev_b32_e32 v36, 1, v11
	v_mov_b32_e32 v37, v16
	s_and_b64 s[4:5], s[4:5], exec
	v_lshl_add_u64 v[34:35], v[34:35], 0, v[36:37]
	v_lshlrev_b32_e32 v36, 4, v33
	s_cselect_b32 s6, 1, 8
	v_ashrrev_i32_e32 v37, 31, v36
	v_cmp_gt_i32_e64 s[40:41], s6, v33
	v_lshl_add_u64 v[36:37], s[44:45], 0, v[36:37]
	v_bfrev_b32_e32 v39, 1
	v_bfrev_b32_e32 v40, 1
	s_and_b64 vcc, exec, s[76:77]
	s_cbranch_vccz .Lhgf_orig
	s_mov_b64 s[100:101], 0x4200
	v_mad_u64_u32 v[252:253], s[8:9], v36, s34, v[34:35]
	v_mad_i32_i24 v253, v37, s34, v253
	v_add_co_u32_e32 v252, vcc, 0x3000, v252
	s_nop 1
	v_addc_co_u32_e32 v253, vcc, 0, v253, vcc
	global_load_ushort v40, v[252:253], off offset:512
	global_load_ushort v38, v[252:253], off offset:-1536
	v_lshl_add_u64 v[252:253], v[252:253], 0, s[100:101]
	global_load_ushort v39, v[252:253], off offset:512
	global_load_ushort v41, v[252:253], off offset:-1536
	v_lshl_add_u64 v[252:253], v[252:253], 0, s[100:101]
	global_load_ushort v42, v[252:253], off offset:512
	global_load_ushort v43, v[252:253], off offset:-1536
	v_lshl_add_u64 v[252:253], v[252:253], 0, s[100:101]
	global_load_ushort v44, v[252:253], off offset:512
	global_load_ushort v48, v[252:253], off offset:-1536
	v_lshl_add_u64 v[252:253], v[252:253], 0, s[100:101]
	global_load_ushort v50, v[252:253], off offset:512
	global_load_ushort v49, v[252:253], off offset:-1536
	v_lshl_add_u64 v[252:253], v[252:253], 0, s[100:101]
	global_load_ushort v51, v[252:253], off offset:512
	global_load_ushort v55, v[252:253], off offset:-1536
	v_lshl_add_u64 v[252:253], v[252:253], 0, s[100:101]
	global_load_ushort v59, v[252:253], off offset:512
	global_load_ushort v54, v[252:253], off offset:-1536
	v_lshl_add_u64 v[252:253], v[252:253], 0, s[100:101]
	global_load_ushort v58, v[252:253], off offset:512
	global_load_ushort v60, v[252:253], off offset:-1536
	v_lshl_add_u64 v[252:253], v[252:253], 0, s[100:101]
	global_load_ushort v65, v[252:253], off offset:512
	global_load_ushort v56, v[252:253], off offset:-1536
	v_lshl_add_u64 v[252:253], v[252:253], 0, s[100:101]
	global_load_ushort v61, v[252:253], off offset:512
	global_load_ushort v67, v[252:253], off offset:-1536
	v_lshl_add_u64 v[252:253], v[252:253], 0, s[100:101]
	global_load_ushort v79, v[252:253], off offset:512
	global_load_ushort v62, v[252:253], off offset:-1536
	v_lshl_add_u64 v[252:253], v[252:253], 0, s[100:101]
	global_load_ushort v68, v[252:253], off offset:512
	global_load_ushort v75, v[252:253], off offset:-1536
	v_lshl_add_u64 v[252:253], v[252:253], 0, s[100:101]
	global_load_ushort v83, v[252:253], off offset:512
	global_load_ushort v71, v[252:253], off offset:-1536
	v_lshl_add_u64 v[252:253], v[252:253], 0, s[100:101]
	global_load_ushort v77, v[252:253], off offset:512
	global_load_ushort v80, v[252:253], off offset:-1536
	v_lshl_add_u64 v[252:253], v[252:253], 0, s[100:101]
	global_load_ushort v102, v[252:253], off offset:512
	global_load_ushort v73, v[252:253], off offset:-1536
	v_lshl_add_u64 v[252:253], v[252:253], 0, s[100:101]
	global_load_ushort v101, v[252:253], off offset:512
	global_load_ushort v105, v[252:253], off offset:-1536
	v_or_b32_e32 v53, 1, v107
	v_lshlrev_b32_e32 v36, 4, v53
	v_ashrrev_i32_e32 v37, 31, v36
	v_cmp_gt_i32_e64 s[42:43], s6, v53
	v_lshl_add_u64 v[36:37], s[44:45], 0, v[36:37]
	v_mad_u64_u32 v[252:253], s[8:9], v36, s34, v[34:35]
	v_mad_i32_i24 v253, v37, s34, v253
	v_add_co_u32_e32 v252, vcc, 0x3000, v252
	s_nop 1
	v_addc_co_u32_e32 v253, vcc, 0, v253, vcc
	global_load_ushort v66, v[252:253], off offset:512
	global_load_ushort v57, v[252:253], off offset:-1536
	v_lshl_add_u64 v[252:253], v[252:253], 0, s[100:101]
	global_load_ushort v64, v[252:253], off offset:512
	global_load_ushort v69, v[252:253], off offset:-1536
	v_lshl_add_u64 v[252:253], v[252:253], 0, s[100:101]
	global_load_ushort v82, v[252:253], off offset:512
	global_load_ushort v63, v[252:253], off offset:-1536
	v_lshl_add_u64 v[252:253], v[252:253], 0, s[100:101]
	global_load_ushort v70, v[252:253], off offset:512
	global_load_ushort v76, v[252:253], off offset:-1536
	v_lshl_add_u64 v[252:253], v[252:253], 0, s[100:101]
; __device__ __forceinline__ float sigm(float x) { return __builtin_amdgcn_rcpf(1.0f + __expf(-x)); }
; __device__ __forceinline__ float sigm(float x) { return __builtin_amdgcn_rcpf(1.0f + __expf(-x)); }
; __device__ __forceinline__ void hg_unit(const Ptrs& P, int l, int b, int hd, int ch, unsigned char* lds, int tid) {
;     ...
;         if (l == 1) { const float a0 = P.lb_logits[hd * 128 + dk], a1 = P.lb_logits[1024 + hd * 128 + dk]; const float mxx = fmaxf(a0, a1); const float e0 = __expf(a0 - mxx), e1 = __expf(a1 - mxx);
;             lb = e1 / (e0 + e1); lb = fminf(fmaxf(lb, 0.f), 1.0f - 1e-4f); }
;         bf16_t hfv[2][16], hqv[2][16];
; #pragma unroll
;         for (int jj = 0; jj < 2; ++jj) { const int j = 2 * sg + jj;
; #pragma unroll
;             for (int t = 0; t < 16; ++t) { hfv[jj][t] = 0; hqv[jj][t] = 0;
;                 if (j < nsub) { const bf16_t* rp = PJ + (row0 + 16 * j + t) * PW + hd * 128 + dk; hfv[jj][t] = rp[C_HF]; hqv[jj][t] = rp[C_HQ]; } } }
; #pragma unroll
;         for (int jj = 0; jj < 2; ++jj) { const int j = 2 * sg + jj;
;             if (j < nsub) {
;                 float kk[16]; float eb = 1.f;
; #pragma unroll
;                 for (int t = 0; t < 16; ++t) {
;                     const float ff = bf2f(hfv[jj][t]); const float qv = bf2f(hqv[jj][t]);
;                     const float sg1 = sigm(ff); const float f = lb + (1.0f - lb) * sg1; eb *= f;
	global_load_ushort v99, v[252:253], off offset:512
	global_load_ushort v72, v[252:253], off offset:-1536
	v_lshl_add_u64 v[252:253], v[252:253], 0, s[100:101]
	global_load_ushort v78, v[252:253], off offset:512
	global_load_ushort v81, v[252:253], off offset:-1536
	v_lshl_add_u64 v[252:253], v[252:253], 0, s[100:101]
	global_load_ushort v104, v[252:253], off offset:512
	global_load_ushort v74, v[252:253], off offset:-1536
	v_lshl_add_u64 v[252:253], v[252:253], 0, s[100:101]
	global_load_ushort v103, v[252:253], off offset:512
	global_load_ushort v109, v[252:253], off offset:-1536
	v_lshl_add_u64 v[252:253], v[252:253], 0, s[100:101]
	global_load_ushort v112, v[252:253], off offset:512
	global_load_ushort v100, v[252:253], off offset:-1536
	v_lshl_add_u64 v[252:253], v[252:253], 0, s[100:101]
	global_load_ushort v110, v[252:253], off offset:512
	global_load_ushort v113, v[252:253], off offset:-1536
	v_lshl_add_u64 v[252:253], v[252:253], 0, s[100:101]
	global_load_ushort v119, v[252:253], off offset:512
	global_load_ushort v111, v[252:253], off offset:-1536
	v_lshl_add_u64 v[252:253], v[252:253], 0, s[100:101]
	global_load_ushort v114, v[252:253], off offset:512
	global_load_ushort v117, v[252:253], off offset:-1536
	v_lshl_add_u64 v[252:253], v[252:253], 0, s[100:101]
	global_load_ushort v121, v[252:253], off offset:512
	global_load_ushort v115, v[252:253], off offset:-1536
	v_lshl_add_u64 v[252:253], v[252:253], 0, s[100:101]
	global_load_ushort v118, v[252:253], off offset:512
	global_load_ushort v120, v[252:253], off offset:-1536
	v_lshl_add_u64 v[252:253], v[252:253], 0, s[100:101]
	global_load_ushort v124, v[252:253], off offset:512
	global_load_ushort v116, v[252:253], off offset:-1536
	v_lshl_add_u64 v[252:253], v[252:253], 0, s[100:101]
	global_load_ushort v122, v[252:253], off offset:512
	global_load_ushort v123, v[252:253], off offset:-1536
	v_readlane_b32 s100, v255, 36
	v_readlane_b32 s101, v255, 37
	s_nop 3
	s_andn2_b64 vcc, exec, s[100:101]
	s_cbranch_vccnz .Lhgf_nolb
	s_waitcnt vmcnt(63)
	v_max_f32_e32 v217, v214, v214
	v_max_f32_e32 v216, v215, v215
	v_max_f32_e32 v216, v217, v216
	v_sub_f32_e32 v217, v214, v216
	v_sub_f32_e32 v32, v215, v216
	v_mul_f32_e32 v217, 0x3fb8aa3b, v217
	v_mul_f32_e32 v32, 0x3fb8aa3b, v32
	v_exp_f32_e32 v217, v217
	v_exp_f32_e32 v32, v32
	s_nop 0
	v_add_f32_e32 v216, v217, v32
	v_div_scale_f32 v217, s[100:101], v216, v216, v32
	v_rcp_f32_e32 v219, v217
	s_nop 0
	v_fma_f32 v220, -v217, v219, 1.0
	v_fmac_f32_e32 v219, v220, v219
	v_div_scale_f32 v220, vcc, v32, v216, v32
	v_mul_f32_e32 v221, v220, v219
	v_fma_f32 v222, -v217, v221, v220
	v_fmac_f32_e32 v221, v222, v219
	v_fma_f32 v217, -v217, v221, v220
	v_div_fmas_f32 v217, v217, v219, v221
	v_div_fixup_f32 v32, v217, v216, v32
	v_max_f32_e32 v32, 0, v32
	v_min_f32_e32 v32, 0x3f7ff972, v32
.Lhgf_nolb:
	s_waitcnt vmcnt(0)
	v_lshlrev_b32_e32 v38, 16, v38
	v_lshlrev_b32_e32 v40, 16, v40
	v_mul_f32_e32 v40, 0xbfb8aa3b, v40
	v_lshlrev_b32_e32 v41, 16, v41
	v_lshlrev_b32_e32 v39, 16, v39
	v_mul_f32_e32 v39, 0xbfb8aa3b, v39
	v_lshlrev_b32_e32 v43, 16, v43
	v_lshlrev_b32_e32 v42, 16, v42
	v_mul_f32_e32 v42, 0xbfb8aa3b, v42
	v_lshlrev_b32_e32 v48, 16, v48
	v_lshlrev_b32_e32 v44, 16, v44
	v_mul_f32_e32 v44, 0xbfb8aa3b, v44
	v_lshlrev_b32_e32 v49, 16, v49
	v_lshlrev_b32_e32 v50, 16, v50
	v_mul_f32_e32 v50, 0xbfb8aa3b, v50
	v_lshlrev_b32_e32 v55, 16, v55
	v_lshlrev_b32_e32 v51, 16, v51
	v_mul_f32_e32 v51, 0xbfb8aa3b, v51
	v_lshlrev_b32_e32 v54, 16, v54
	v_lshlrev_b32_e32 v59, 16, v59
	v_mul_f32_e32 v59, 0xbfb8aa3b, v59
	v_lshlrev_b32_e32 v60, 16, v60
	v_lshlrev_b32_e32 v58, 16, v58
	v_mul_f32_e32 v58, 0xbfb8aa3b, v58
	v_lshlrev_b32_e32 v56, 16, v56
	v_lshlrev_b32_e32 v65, 16, v65
	v_mul_f32_e32 v65, 0xbfb8aa3b, v65
	v_lshlrev_b32_e32 v67, 16, v67
	v_lshlrev_b32_e32 v61, 16, v61
	v_mul_f32_e32 v61, 0xbfb8aa3b, v61
	v_lshlrev_b32_e32 v62, 16, v62
	v_lshlrev_b32_e32 v79, 16, v79
	v_mul_f32_e32 v79, 0xbfb8aa3b, v79
	v_lshlrev_b32_e32 v75, 16, v75
	v_lshlrev_b32_e32 v68, 16, v68
	v_mul_f32_e32 v68, 0xbfb8aa3b, v68
	v_lshlrev_b32_e32 v71, 16, v71
	v_lshlrev_b32_e32 v83, 16, v83
	v_mul_f32_e32 v83, 0xbfb8aa3b, v83
	v_lshlrev_b32_e32 v80, 16, v80
	v_lshlrev_b32_e32 v77, 16, v77
	v_mul_f32_e32 v77, 0xbfb8aa3b, v77
	v_lshlrev_b32_e32 v73, 16, v73
	v_lshlrev_b32_e32 v102, 16, v102
	v_mul_f32_e32 v102, 0xbfb8aa3b, v102
	v_lshlrev_b32_e32 v105, 16, v105
	v_lshlrev_b32_e32 v101, 16, v101
	v_mul_f32_e32 v101, 0xbfb8aa3b, v101
	v_lshlrev_b32_e32 v57, 16, v57
	v_lshlrev_b32_e32 v66, 16, v66
	v_mul_f32_e32 v66, 0xbfb8aa3b, v66
	v_lshlrev_b32_e32 v69, 16, v69
	v_lshlrev_b32_e32 v64, 16, v64
	v_mul_f32_e32 v64, 0xbfb8aa3b, v64
	v_lshlrev_b32_e32 v63, 16, v63
	v_lshlrev_b32_e32 v82, 16, v82
	v_mul_f32_e32 v82, 0xbfb8aa3b, v82
	v_lshlrev_b32_e32 v76, 16, v76
	v_lshlrev_b32_e32 v70, 16, v70
	v_mul_f32_e32 v70, 0xbfb8aa3b, v70
	v_lshlrev_b32_e32 v72, 16, v72
	v_lshlrev_b32_e32 v99, 16, v99
	v_mul_f32_e32 v99, 0xbfb8aa3b, v99
	v_lshlrev_b32_e32 v81, 16, v81
	v_lshlrev_b32_e32 v78, 16, v78
	v_mul_f32_e32 v78, 0xbfb8aa3b, v78
	v_lshlrev_b32_e32 v74, 16, v74
	v_lshlrev_b32_e32 v104, 16, v104
	v_mul_f32_e32 v104, 0xbfb8aa3b, v104
	v_lshlrev_b32_e32 v109, 16, v109
	v_lshlrev_b32_e32 v103, 16, v103
	v_mul_f32_e32 v103, 0xbfb8aa3b, v103
	v_lshlrev_b32_e32 v100, 16, v100
	v_lshlrev_b32_e32 v112, 16, v112
	v_mul_f32_e32 v112, 0xbfb8aa3b, v112
	v_lshlrev_b32_e32 v113, 16, v113
	v_lshlrev_b32_e32 v110, 16, v110
	v_mul_f32_e32 v110, 0xbfb8aa3b, v110
	v_lshlrev_b32_e32 v111, 16, v111
	v_lshlrev_b32_e32 v119, 16, v119
	v_mul_f32_e32 v119, 0xbfb8aa3b, v119
	v_lshlrev_b32_e32 v117, 16, v117
	v_lshlrev_b32_e32 v114, 16, v114
	v_mul_f32_e32 v114, 0xbfb8aa3b, v114
	v_lshlrev_b32_e32 v115, 16, v115
	v_lshlrev_b32_e32 v121, 16, v121
	v_mul_f32_e32 v121, 0xbfb8aa3b, v121
	v_lshlrev_b32_e32 v120, 16, v120
	v_lshlrev_b32_e32 v118, 16, v118
	v_mul_f32_e32 v118, 0xbfb8aa3b, v118
	v_lshlrev_b32_e32 v116, 16, v116
	v_lshlrev_b32_e32 v124, 16, v124
	v_mul_f32_e32 v124, 0xbfb8aa3b, v124
	v_lshlrev_b32_e32 v123, 16, v123
	v_lshlrev_b32_e32 v122, 16, v122
	v_mul_f32_e32 v122, 0xbfb8aa3b, v122
	s_branch .Lhgf_join
